# P9 EpiGu: scalar -log2e multiplies and +1.0 adds packed into v_pk_mul_f32 / v_pk_add_f32 (bit-identical)
# baseline (speedup 1.0000x reference)
.LBB0_1243:
	ds_read_b128 v[170:173], v162
	ds_read_b128 v[174:177], v162 offset:1024
	ds_read_b128 v[178:181], v162 offset:2048
	ds_read_b128 v[182:185], v162 offset:3072
	s_add_u32 s34, s30, 0xfffc0080
	s_addc_u32 s35, s31, -1
	s_cmp_eq_u32 s41, 12
	s_cselect_b32 s37, s11, s35
	s_cselect_b32 s36, s17, s34
	s_cselect_b32 s35, s29, s40
	s_cselect_b32 s34, s38, s39
	v_lshl_add_u64 v[144:145], s[30:31], 0, v[134:135]
	s_add_i32 m0, s48, 0xc000
	ds_read_b128 v[186:189], v163
	ds_read_b128 v[190:193], v163 offset:1024
	ds_read_b128 v[194:197], v163 offset:2048
	ds_read_b128 v[198:201], v163 offset:3072
	ds_read_b128 v[204:207], v163 offset:4096
	ds_read_b128 v[208:211], v163 offset:5120
	ds_read_b128 v[212:215], v163 offset:6144
	ds_read_b128 v[216:219], v163 offset:7168
	global_load_lds_dwordx4 v[144:145], off
	v_lshl_add_u64 v[144:145], s[30:31], 0, v[136:137]
	s_add_i32 m0, s48, 0xe000
	s_nop 0
	global_load_lds_dwordx4 v[144:145], off
	ds_read_b128 v[220:223], v164
	ds_read_b128 v[224:227], v164 offset:1024
	ds_read_b128 v[228:231], v164 offset:2048
	ds_read_b128 v[232:235], v164 offset:3072
	s_waitcnt lgkmcnt(0)
	s_waitcnt vmcnt(8)
	s_barrier
	s_setprio 1
	v_mfma_f32_16x16x32_bf16 v[124:127], v[170:173], v[186:189], v[124:127]
	v_mfma_f32_16x16x32_bf16 v[120:123], v[178:181], v[186:189], v[120:123]
	v_mfma_f32_16x16x32_bf16 v[112:115], v[170:173], v[194:197], v[112:115]
	v_mfma_f32_16x16x32_bf16 v[104:107], v[178:181], v[194:197], v[104:107]
	v_mfma_f32_16x16x32_bf16 v[96:99], v[170:173], v[204:207], v[96:99]
	v_mfma_f32_16x16x32_bf16 v[88:91], v[178:181], v[204:207], v[88:91]
	v_mfma_f32_16x16x32_bf16 v[80:83], v[170:173], v[212:215], v[80:83]
	v_mfma_f32_16x16x32_bf16 v[72:75], v[178:181], v[212:215], v[72:75]
	v_mfma_f32_16x16x32_bf16 v[124:127], v[174:177], v[190:193], v[124:127]
	v_mfma_f32_16x16x32_bf16 v[120:123], v[182:185], v[190:193], v[120:123]
	v_mfma_f32_16x16x32_bf16 v[112:115], v[174:177], v[198:201], v[112:115]
	v_mfma_f32_16x16x32_bf16 v[104:107], v[182:185], v[198:201], v[104:107]
	v_mfma_f32_16x16x32_bf16 v[96:99], v[174:177], v[208:211], v[96:99]
	v_mfma_f32_16x16x32_bf16 v[88:91], v[182:185], v[208:211], v[88:91]
	v_mfma_f32_16x16x32_bf16 v[80:83], v[174:177], v[216:219], v[80:83]
	v_mfma_f32_16x16x32_bf16 v[72:75], v[182:185], v[216:219], v[72:75]
	v_mfma_f32_16x16x32_bf16 v[116:119], v[220:223], v[186:189], v[116:119]
	v_mfma_f32_16x16x32_bf16 v[108:111], v[228:231], v[186:189], v[108:111]
	v_mfma_f32_16x16x32_bf16 v[100:103], v[220:223], v[194:197], v[100:103]
	v_mfma_f32_16x16x32_bf16 v[92:95], v[228:231], v[194:197], v[92:95]
	v_mfma_f32_16x16x32_bf16 v[84:87], v[220:223], v[204:207], v[84:87]
	v_mfma_f32_16x16x32_bf16 v[76:79], v[228:231], v[204:207], v[76:79]
	v_mfma_f32_16x16x32_bf16 v[68:71], v[220:223], v[212:215], v[68:71]
	v_mfma_f32_16x16x32_bf16 v[64:67], v[228:231], v[212:215], v[64:67]
	v_mfma_f32_16x16x32_bf16 v[116:119], v[224:227], v[190:193], v[116:119]
	v_mfma_f32_16x16x32_bf16 v[108:111], v[232:235], v[190:193], v[108:111]
	v_mfma_f32_16x16x32_bf16 v[100:103], v[224:227], v[198:201], v[100:103]
	v_mfma_f32_16x16x32_bf16 v[92:95], v[232:235], v[198:201], v[92:95]
	v_mfma_f32_16x16x32_bf16 v[84:87], v[224:227], v[208:211], v[84:87]
	v_mfma_f32_16x16x32_bf16 v[76:79], v[232:235], v[208:211], v[76:79]
	v_mfma_f32_16x16x32_bf16 v[68:71], v[224:227], v[216:219], v[68:71]
	v_mfma_f32_16x16x32_bf16 v[64:67], v[232:235], v[216:219], v[64:67]
	s_setprio 0
	s_barrier
	ds_read_b128 v[186:189], v163 offset:16384
	ds_read_b128 v[190:193], v163 offset:17408
	ds_read_b128 v[194:197], v163 offset:18432
	ds_read_b128 v[198:201], v163 offset:19456
	ds_read_b128 v[204:207], v163 offset:20480
	ds_read_b128 v[208:211], v163 offset:21504
	ds_read_b128 v[212:215], v163 offset:22528
	ds_read_b128 v[216:219], v163 offset:23552
	s_mov_b32 m0, s46
	v_lshl_add_u64 v[144:145], s[34:35], 0, v[128:129]
	global_load_lds_dwordx4 v[144:145], off
	v_lshl_add_u64 v[236:237], s[34:35], 0, v[130:131]
	s_mov_b32 m0, s47
	s_nop 0
	global_load_lds_dwordx4 v[236:237], off
	s_mov_b32 m0, s48
	v_lshl_add_u64 v[238:239], s[36:37], 0, v[128:129]
	global_load_lds_dwordx4 v[238:239], off
	v_lshl_add_u64 v[240:241], s[36:37], 0, v[130:131]
	s_mov_b32 m0, s49
	s_nop 0
	global_load_lds_dwordx4 v[240:241], off
	s_add_u32 s72, s34, 0x40000
	s_addc_u32 s73, s35, 0
	s_mov_b32 m0, s50
	v_lshl_add_u64 v[248:249], s[72:73], 0, v[128:129]
	global_load_lds_dwordx4 v[248:249], off
	v_lshl_add_u64 v[248:249], s[72:73], 0, v[130:131]
	s_mov_b32 m0, s51
	s_nop 0
	global_load_lds_dwordx4 v[248:249], off
	s_waitcnt lgkmcnt(0)
	s_waitcnt vmcnt(8)
	s_barrier
	s_setprio 1
	v_mfma_f32_16x16x32_bf16 v[60:63], v[170:173], v[186:189], v[60:63]
	v_mfma_f32_16x16x32_bf16 v[56:59], v[178:181], v[186:189], v[56:59]
	v_mfma_f32_16x16x32_bf16 v[48:51], v[170:173], v[194:197], v[48:51]
	v_mfma_f32_16x16x32_bf16 v[40:43], v[178:181], v[194:197], v[40:43]
	v_mfma_f32_16x16x32_bf16 v[32:35], v[170:173], v[204:207], v[32:35]
	v_mfma_f32_16x16x32_bf16 v[24:27], v[178:181], v[204:207], v[24:27]
	v_mfma_f32_16x16x32_bf16 v[16:19], v[170:173], v[212:215], v[16:19]
	v_mfma_f32_16x16x32_bf16 v[8:11], v[178:181], v[212:215], v[8:11]
	v_mfma_f32_16x16x32_bf16 v[60:63], v[174:177], v[190:193], v[60:63]
	v_mfma_f32_16x16x32_bf16 v[56:59], v[182:185], v[190:193], v[56:59]
	v_mfma_f32_16x16x32_bf16 v[48:51], v[174:177], v[198:201], v[48:51]
	v_mfma_f32_16x16x32_bf16 v[40:43], v[182:185], v[198:201], v[40:43]
	v_mfma_f32_16x16x32_bf16 v[32:35], v[174:177], v[208:211], v[32:35]
	v_mfma_f32_16x16x32_bf16 v[24:27], v[182:185], v[208:211], v[24:27]
	v_mfma_f32_16x16x32_bf16 v[16:19], v[174:177], v[216:219], v[16:19]
	v_mfma_f32_16x16x32_bf16 v[8:11], v[182:185], v[216:219], v[8:11]
	v_mfma_f32_16x16x32_bf16 v[52:55], v[220:223], v[186:189], v[52:55]
	v_mfma_f32_16x16x32_bf16 v[44:47], v[228:231], v[186:189], v[44:47]
	v_mfma_f32_16x16x32_bf16 v[36:39], v[220:223], v[194:197], v[36:39]
	v_mfma_f32_16x16x32_bf16 v[28:31], v[228:231], v[194:197], v[28:31]
	v_mfma_f32_16x16x32_bf16 v[20:23], v[220:223], v[204:207], v[20:23]
	v_mfma_f32_16x16x32_bf16 v[12:15], v[228:231], v[204:207], v[12:15]
	v_mfma_f32_16x16x32_bf16 v[4:7], v[220:223], v[212:215], v[4:7]
	v_mfma_f32_16x16x32_bf16 v[0:3], v[228:231], v[212:215], v[0:3]
	v_mfma_f32_16x16x32_bf16 v[52:55], v[224:227], v[190:193], v[52:55]
	v_mfma_f32_16x16x32_bf16 v[44:47], v[232:235], v[190:193], v[44:47]
	v_mfma_f32_16x16x32_bf16 v[36:39], v[224:227], v[198:201], v[36:39]
	v_mfma_f32_16x16x32_bf16 v[28:31], v[232:235], v[198:201], v[28:31]
	v_mfma_f32_16x16x32_bf16 v[20:23], v[224:227], v[208:211], v[20:23]
	v_mfma_f32_16x16x32_bf16 v[12:15], v[232:235], v[208:211], v[12:15]
	v_mfma_f32_16x16x32_bf16 v[4:7], v[224:227], v[216:219], v[4:7]
	v_mfma_f32_16x16x32_bf16 v[0:3], v[232:235], v[216:219], v[0:3]
	s_setprio 0
	s_barrier
	ds_read_b128 v[170:173], v165
	ds_read_b128 v[174:177], v165 offset:1024
	ds_read_b128 v[178:181], v165 offset:2048
	ds_read_b128 v[182:185], v165 offset:3072
	s_add_u32 s36, s36, 0x40000
	s_addc_u32 s37, s37, 0
	s_mov_b32 m0, s52
	v_lshl_add_u64 v[220:221], s[36:37], 0, v[128:129]
	ds_read_b128 v[186:189], v163 offset:32768
	ds_read_b128 v[190:193], v163 offset:33792
	ds_read_b128 v[194:197], v163 offset:34816
	ds_read_b128 v[198:201], v163 offset:35840
	ds_read_b128 v[204:207], v163 offset:36864
	ds_read_b128 v[208:211], v163 offset:37888
	ds_read_b128 v[212:215], v163 offset:38912
	ds_read_b128 v[216:219], v163 offset:39936
	global_load_lds_dwordx4 v[220:221], off
	v_lshl_add_u64 v[220:221], s[36:37], 0, v[130:131]
	s_mov_b32 m0, s53
	s_nop 0
	global_load_lds_dwordx4 v[220:221], off
	ds_read_b128 v[220:223], v166
	ds_read_b128 v[224:227], v166 offset:1024
	ds_read_b128 v[228:231], v166 offset:2048
	ds_read_b128 v[232:235], v166 offset:3072
	s_waitcnt lgkmcnt(0)
	s_waitcnt vmcnt(8)
	s_barrier
	s_setprio 1
	v_mfma_f32_16x16x32_bf16 v[124:127], v[170:173], v[186:189], v[124:127]
	v_mfma_f32_16x16x32_bf16 v[120:123], v[178:181], v[186:189], v[120:123]
	v_mfma_f32_16x16x32_bf16 v[112:115], v[170:173], v[194:197], v[112:115]
	v_mfma_f32_16x16x32_bf16 v[104:107], v[178:181], v[194:197], v[104:107]
	v_mfma_f32_16x16x32_bf16 v[96:99], v[170:173], v[204:207], v[96:99]
	v_mfma_f32_16x16x32_bf16 v[88:91], v[178:181], v[204:207], v[88:91]
	v_mfma_f32_16x16x32_bf16 v[80:83], v[170:173], v[212:215], v[80:83]
	v_mfma_f32_16x16x32_bf16 v[72:75], v[178:181], v[212:215], v[72:75]
	v_mfma_f32_16x16x32_bf16 v[124:127], v[174:177], v[190:193], v[124:127]
	v_mfma_f32_16x16x32_bf16 v[120:123], v[182:185], v[190:193], v[120:123]
	v_mfma_f32_16x16x32_bf16 v[112:115], v[174:177], v[198:201], v[112:115]
	v_mfma_f32_16x16x32_bf16 v[104:107], v[182:185], v[198:201], v[104:107]
	v_mfma_f32_16x16x32_bf16 v[96:99], v[174:177], v[208:211], v[96:99]
	v_mfma_f32_16x16x32_bf16 v[88:91], v[182:185], v[208:211], v[88:91]
	v_mfma_f32_16x16x32_bf16 v[80:83], v[174:177], v[216:219], v[80:83]
	v_mfma_f32_16x16x32_bf16 v[72:75], v[182:185], v[216:219], v[72:75]
	v_mfma_f32_16x16x32_bf16 v[116:119], v[220:223], v[186:189], v[116:119]
	v_mfma_f32_16x16x32_bf16 v[108:111], v[228:231], v[186:189], v[108:111]
	v_mfma_f32_16x16x32_bf16 v[100:103], v[220:223], v[194:197], v[100:103]
	v_mfma_f32_16x16x32_bf16 v[92:95], v[228:231], v[194:197], v[92:95]
	v_mfma_f32_16x16x32_bf16 v[84:87], v[220:223], v[204:207], v[84:87]
	v_mfma_f32_16x16x32_bf16 v[76:79], v[228:231], v[204:207], v[76:79]
	v_mfma_f32_16x16x32_bf16 v[68:71], v[220:223], v[212:215], v[68:71]
	v_mfma_f32_16x16x32_bf16 v[64:67], v[228:231], v[212:215], v[64:67]
	v_mfma_f32_16x16x32_bf16 v[116:119], v[224:227], v[190:193], v[116:119]
	v_mfma_f32_16x16x32_bf16 v[108:111], v[232:235], v[190:193], v[108:111]
	v_mfma_f32_16x16x32_bf16 v[100:103], v[224:227], v[198:201], v[100:103]
	v_mfma_f32_16x16x32_bf16 v[92:95], v[232:235], v[198:201], v[92:95]
	v_mfma_f32_16x16x32_bf16 v[84:87], v[224:227], v[208:211], v[84:87]
	v_mfma_f32_16x16x32_bf16 v[76:79], v[232:235], v[208:211], v[76:79]
	v_mfma_f32_16x16x32_bf16 v[68:71], v[224:227], v[216:219], v[68:71]
	v_mfma_f32_16x16x32_bf16 v[64:67], v[232:235], v[216:219], v[64:67]
	s_setprio 0
	s_barrier
	ds_read_b128 v[186:189], v163 offset:49152
	ds_read_b128 v[190:193], v163 offset:50176
	ds_read_b128 v[194:197], v163 offset:51200
	ds_read_b128 v[198:201], v163 offset:52224
	ds_read_b128 v[204:207], v163 offset:53248
	ds_read_b128 v[208:211], v163 offset:54272
	ds_read_b128 v[212:215], v163 offset:55296
	ds_read_b128 v[216:219], v163 offset:56320
	s_mov_b32 m0, s54
	v_lshl_add_u64 v[144:145], v[144:145], 0, s[12:13]
	global_load_lds_dwordx4 v[144:145], off
	v_lshl_add_u64 v[144:145], v[236:237], 0, s[12:13]
	s_mov_b32 m0, s55
	s_nop 0
	global_load_lds_dwordx4 v[144:145], off
	s_mov_b32 m0, s56
	v_lshl_add_u64 v[144:145], v[238:239], 0, s[12:13]
	global_load_lds_dwordx4 v[144:145], off
	v_lshl_add_u64 v[144:145], v[240:241], 0, s[12:13]
	s_mov_b32 m0, s57
	s_nop 0
	global_load_lds_dwordx4 v[144:145], off
	s_add_u32 s34, s34, 0x40080
	s_addc_u32 s35, s35, 0
	s_mov_b32 m0, s58
	v_lshl_add_u64 v[144:145], s[34:35], 0, v[128:129]
	global_load_lds_dwordx4 v[144:145], off
	v_lshl_add_u64 v[144:145], s[34:35], 0, v[130:131]
	s_mov_b32 m0, s59
	s_nop 0
	global_load_lds_dwordx4 v[144:145], off
	s_waitcnt lgkmcnt(0)
	s_waitcnt vmcnt(8)
	s_barrier
	s_setprio 1
	v_mfma_f32_16x16x32_bf16 v[60:63], v[170:173], v[186:189], v[60:63]
	v_mfma_f32_16x16x32_bf16 v[56:59], v[178:181], v[186:189], v[56:59]
	v_mfma_f32_16x16x32_bf16 v[48:51], v[170:173], v[194:197], v[48:51]
	v_mfma_f32_16x16x32_bf16 v[40:43], v[178:181], v[194:197], v[40:43]
	v_mfma_f32_16x16x32_bf16 v[32:35], v[170:173], v[204:207], v[32:35]
	v_mfma_f32_16x16x32_bf16 v[24:27], v[178:181], v[204:207], v[24:27]
	v_mfma_f32_16x16x32_bf16 v[16:19], v[170:173], v[212:215], v[16:19]
	v_mfma_f32_16x16x32_bf16 v[8:11], v[178:181], v[212:215], v[8:11]
	v_mfma_f32_16x16x32_bf16 v[60:63], v[174:177], v[190:193], v[60:63]
	v_mfma_f32_16x16x32_bf16 v[56:59], v[182:185], v[190:193], v[56:59]
	v_mfma_f32_16x16x32_bf16 v[48:51], v[174:177], v[198:201], v[48:51]
	v_mfma_f32_16x16x32_bf16 v[40:43], v[182:185], v[198:201], v[40:43]
	v_mfma_f32_16x16x32_bf16 v[32:35], v[174:177], v[208:211], v[32:35]
	v_mfma_f32_16x16x32_bf16 v[24:27], v[182:185], v[208:211], v[24:27]
	v_mfma_f32_16x16x32_bf16 v[16:19], v[174:177], v[216:219], v[16:19]
	v_mfma_f32_16x16x32_bf16 v[8:11], v[182:185], v[216:219], v[8:11]
	v_mfma_f32_16x16x32_bf16 v[52:55], v[220:223], v[186:189], v[52:55]
	v_mfma_f32_16x16x32_bf16 v[44:47], v[228:231], v[186:189], v[44:47]
	v_mfma_f32_16x16x32_bf16 v[36:39], v[220:223], v[194:197], v[36:39]
	v_mfma_f32_16x16x32_bf16 v[28:31], v[228:231], v[194:197], v[28:31]
	v_mfma_f32_16x16x32_bf16 v[20:23], v[220:223], v[204:207], v[20:23]
	v_mfma_f32_16x16x32_bf16 v[12:15], v[228:231], v[204:207], v[12:15]
	v_mfma_f32_16x16x32_bf16 v[4:7], v[220:223], v[212:215], v[4:7]
	v_mfma_f32_16x16x32_bf16 v[0:3], v[228:231], v[212:215], v[0:3]
	v_mfma_f32_16x16x32_bf16 v[52:55], v[224:227], v[190:193], v[52:55]
	v_mfma_f32_16x16x32_bf16 v[44:47], v[232:235], v[190:193], v[44:47]
	v_mfma_f32_16x16x32_bf16 v[36:39], v[224:227], v[198:201], v[36:39]
	v_mfma_f32_16x16x32_bf16 v[28:31], v[232:235], v[198:201], v[28:31]
	v_mfma_f32_16x16x32_bf16 v[20:23], v[224:227], v[208:211], v[20:23]
	v_mfma_f32_16x16x32_bf16 v[12:15], v[232:235], v[208:211], v[12:15]
	v_mfma_f32_16x16x32_bf16 v[4:7], v[224:227], v[216:219], v[4:7]
	v_mfma_f32_16x16x32_bf16 v[0:3], v[232:235], v[216:219], v[0:3]
	s_setprio 0
	s_add_i32 s41, s41, 2
	s_add_u32 s30, s30, 0x100
	s_addc_u32 s31, s31, 0
	s_add_u32 s39, s39, 0x100
	s_addc_u32 s40, s40, 0
	s_cmp_gt_u32 s41, 13
	s_barrier
	s_cbranch_scc0 .LBB0_1243
	v_lshlrev_b32_e32 v170, 2, v160
	v_add_u32_e32 v170, s92, v170
	ds_read_b32 v174, v170
	ds_read_b32 v176, v170 offset:64
	ds_read_b32 v156, v170 offset:128
	ds_read_b32 v154, v170 offset:192
	ds_read_b32 v152, v170 offset:512
	ds_read_b32 v150, v170 offset:576
	ds_read_b32 v148, v170 offset:640
	ds_read_b32 v146, v170 offset:704
	v_lshl_add_u32 v144, s42, 8, v160
	v_add_u32_e32 v145, 0x80, v144
	s_cmpk_lt_i32 s42, 0x80
	v_mov_b32_e32 v190, 0xbfb8aa3b
	v_mov_b32_e32 v192, 1.0
	s_waitcnt lgkmcnt(0)
	v_pk_mul_f32 v[124:125], v[124:125], v[174:175] op_sel_hi:[1,0]
	v_mul_f32_e32 v172, 0xbfb8aa3b, v125
	v_exp_f32_e32 v173, v172
	v_mul_f32_e32 v169, 0xbfb8aa3b, v124
	v_exp_f32_e32 v169, v169
	v_pk_mul_f32 v[126:127], v[126:127], v[174:175] op_sel_hi:[1,0]
	v_pk_mul_f32 v[118:119], v[118:119], v[174:175] op_sel_hi:[1,0]
	v_add_f32_e32 v169, 1.0, v169
	v_rcp_f32_e32 v172, v169
	v_add_f32_e32 v169, 1.0, v173
	v_mul_f32_e32 v173, 0xbfb8aa3b, v126
	v_exp_f32_e32 v175, v173
	v_mul_f32_e32 v173, 0xbfb8aa3b, v127
	v_exp_f32_e32 v177, v173
	v_rcp_f32_e32 v173, v169
	v_add_f32_e32 v169, 1.0, v175
	v_rcp_f32_e32 v178, v169
	v_add_f32_e32 v169, 1.0, v177
	v_rcp_f32_e32 v179, v169
	v_pk_mul_f32 v[116:117], v[116:117], v[174:175] op_sel_hi:[1,0]
	v_pk_mul_f32 v[124:125], v[124:125], v[172:173]
	v_pk_mul_f32 v[120:121], v[120:121], v[174:175] op_sel_hi:[1,0]
	v_pk_mul_f32 v[116:117], v[116:117], v[124:125]
	v_pk_mul_f32 v[124:125], v[126:127], v[178:179]
	v_pk_mul_f32 v[122:123], v[122:123], v[174:175] op_sel_hi:[1,0]
	v_pk_mul_f32 v[118:119], v[118:119], v[124:125]
	v_pk_mul_f32 v[124:125], v[120:121], v[190:191] op_sel_hi:[1,0]
	v_exp_f32_e32 v124, v124
	v_exp_f32_e32 v125, v125
	v_pk_mul_f32 v[126:127], v[122:123], v[190:191] op_sel_hi:[1,0]
	v_exp_f32_e32 v126, v126
	v_exp_f32_e32 v127, v127
	v_pk_add_f32 v[124:125], v[124:125], v[192:193] op_sel_hi:[1,0]
	v_rcp_f32_e32 v124, v124
	v_rcp_f32_e32 v125, v125
	v_pk_add_f32 v[126:127], v[126:127], v[192:193] op_sel_hi:[1,0]
	v_rcp_f32_e32 v126, v126
	v_rcp_f32_e32 v127, v127
	v_pk_mul_f32 v[108:109], v[108:109], v[174:175] op_sel_hi:[1,0]
	v_pk_mul_f32 v[120:121], v[120:121], v[124:125]
	v_lshl_or_b32 v170, s28, 7, v161
	v_pk_mul_f32 v[110:111], v[110:111], v[174:175] op_sel_hi:[1,0]
	v_pk_mul_f32 v[108:109], v[108:109], v[120:121]
	v_pk_mul_f32 v[120:121], v[122:123], v[126:127]
	v_ashrrev_i32_e32 v171, 31, v170
	v_pk_mul_f32 v[110:111], v[110:111], v[120:121]
	v_cvt_pk_bf16_f32 v116, v116, v117
	v_cvt_pk_bf16_f32 v117, v118, v119
	v_cvt_pk_bf16_f32 v118, v108, v109
	v_mov_b64_e32 v[108:109], s[6:7]
	v_cvt_pk_bf16_f32 v119, v110, v111
	v_mad_i64_i32 v[120:121], s[28:29], v144, s68, v[108:109]
	v_lshlrev_b64 v[110:111], 1, v[170:171]
	v_lshl_add_u64 v[120:121], v[120:121], 0, v[110:111]
	v_pk_mul_f32 v[112:113], v[112:113], v[176:177] op_sel_hi:[1,0]
	global_store_dwordx4 v[120:121], v[116:119], off
	v_pk_mul_f32 v[114:115], v[114:115], v[176:177] op_sel_hi:[1,0]
	v_pk_mul_f32 v[100:101], v[100:101], v[176:177] op_sel_hi:[1,0]
	v_pk_mul_f32 v[116:117], v[112:113], v[190:191] op_sel_hi:[1,0]
	v_exp_f32_e32 v116, v116
	v_exp_f32_e32 v117, v117
	v_pk_mul_f32 v[118:119], v[114:115], v[190:191] op_sel_hi:[1,0]
	v_exp_f32_e32 v118, v118
	v_exp_f32_e32 v119, v119
	v_pk_add_f32 v[116:117], v[116:117], v[192:193] op_sel_hi:[1,0]
	v_rcp_f32_e32 v116, v116
	v_rcp_f32_e32 v117, v117
	v_pk_add_f32 v[118:119], v[118:119], v[192:193] op_sel_hi:[1,0]
	v_rcp_f32_e32 v118, v118
	v_rcp_f32_e32 v119, v119
	v_pk_mul_f32 v[112:113], v[112:113], v[116:117]
	v_pk_mul_f32 v[102:103], v[102:103], v[176:177] op_sel_hi:[1,0]
	v_pk_mul_f32 v[100:101], v[100:101], v[112:113]
	v_pk_mul_f32 v[112:113], v[114:115], v[118:119]
	v_pk_mul_f32 v[104:105], v[104:105], v[176:177] op_sel_hi:[1,0]
	v_pk_mul_f32 v[102:103], v[102:103], v[112:113]
	v_pk_mul_f32 v[106:107], v[106:107], v[176:177] op_sel_hi:[1,0]
	v_pk_mul_f32 v[112:113], v[104:105], v[190:191] op_sel_hi:[1,0]
	v_exp_f32_e32 v112, v112
	v_exp_f32_e32 v113, v113
	v_pk_mul_f32 v[114:115], v[106:107], v[190:191] op_sel_hi:[1,0]
	v_exp_f32_e32 v114, v114
	v_exp_f32_e32 v115, v115
	v_pk_add_f32 v[112:113], v[112:113], v[192:193] op_sel_hi:[1,0]
	v_rcp_f32_e32 v112, v112
	v_rcp_f32_e32 v113, v113
	v_pk_add_f32 v[114:115], v[114:115], v[192:193] op_sel_hi:[1,0]
	v_rcp_f32_e32 v114, v114
	v_rcp_f32_e32 v115, v115
	v_pk_mul_f32 v[92:93], v[92:93], v[176:177] op_sel_hi:[1,0]
	v_pk_mul_f32 v[104:105], v[104:105], v[112:113]
	v_pk_mul_f32 v[94:95], v[94:95], v[176:177] op_sel_hi:[1,0]
	v_pk_mul_f32 v[104:105], v[92:93], v[104:105]
	v_pk_mul_f32 v[92:93], v[106:107], v[114:115]
	v_or_b32_e32 v112, 16, v144
	v_pk_mul_f32 v[106:107], v[94:95], v[92:93]
	v_cvt_pk_bf16_f32 v92, v100, v101
	v_mad_i64_i32 v[100:101], s[28:29], v112, s68, v[108:109]
	v_cvt_pk_bf16_f32 v93, v102, v103
	v_cvt_pk_bf16_f32 v94, v104, v105
	v_cvt_pk_bf16_f32 v95, v106, v107
	v_lshl_add_u64 v[100:101], v[100:101], 0, v[110:111]
	global_store_dwordx4 v[100:101], v[92:95], off
	v_pk_mul_f32 v[86:87], v[86:87], v[156:157] op_sel_hi:[1,0]
	v_pk_mul_f32 v[88:89], v[88:89], v[156:157] op_sel_hi:[1,0]
	v_pk_mul_f32 v[92:93], v[98:99], v[156:157] op_sel_hi:[1,0]
	v_pk_mul_f32 v[94:95], v[96:97], v[156:157] op_sel_hi:[1,0]
	v_pk_mul_f32 v[98:99], v[92:93], v[190:191] op_sel_hi:[1,0]
	v_pk_mul_f32 v[96:97], v[94:95], v[190:191] op_sel_hi:[1,0]
	v_exp_f32_e32 v98, v98
	v_exp_f32_e32 v99, v99
	v_exp_f32_e32 v96, v96
	v_exp_f32_e32 v97, v97
	v_pk_add_f32 v[98:99], v[98:99], v[192:193] op_sel_hi:[1,0]
	v_pk_add_f32 v[96:97], v[96:97], v[192:193] op_sel_hi:[1,0]
	v_rcp_f32_e32 v98, v98
	v_rcp_f32_e32 v99, v99
	v_rcp_f32_e32 v96, v96
	v_rcp_f32_e32 v97, v97
	v_pk_mul_f32 v[84:85], v[84:85], v[156:157] op_sel_hi:[1,0]
	v_pk_mul_f32 v[92:93], v[92:93], v[98:99]
	v_pk_mul_f32 v[90:91], v[90:91], v[156:157] op_sel_hi:[1,0]
	v_pk_mul_f32 v[94:95], v[94:95], v[96:97]
	v_pk_mul_f32 v[86:87], v[86:87], v[92:93]
	v_pk_mul_f32 v[92:93], v[88:89], v[190:191] op_sel_hi:[1,0]
	v_pk_mul_f32 v[84:85], v[84:85], v[94:95]
	v_exp_f32_e32 v92, v92
	v_exp_f32_e32 v93, v93
	v_pk_mul_f32 v[94:95], v[90:91], v[190:191] op_sel_hi:[1,0]
	v_exp_f32_e32 v94, v94
	v_exp_f32_e32 v95, v95
	v_pk_add_f32 v[92:93], v[92:93], v[192:193] op_sel_hi:[1,0]
	v_rcp_f32_e32 v92, v92
	v_rcp_f32_e32 v93, v93
	v_pk_add_f32 v[94:95], v[94:95], v[192:193] op_sel_hi:[1,0]
	v_rcp_f32_e32 v94, v94
	v_rcp_f32_e32 v95, v95
	v_pk_mul_f32 v[76:77], v[76:77], v[156:157] op_sel_hi:[1,0]
	v_pk_mul_f32 v[88:89], v[88:89], v[92:93]
	v_pk_mul_f32 v[78:79], v[78:79], v[156:157] op_sel_hi:[1,0]
	v_pk_mul_f32 v[88:89], v[76:77], v[88:89]
	v_pk_mul_f32 v[76:77], v[90:91], v[94:95]
	v_or_b32_e32 v92, 32, v144
	v_pk_mul_f32 v[90:91], v[78:79], v[76:77]
	v_cvt_pk_bf16_f32 v76, v84, v85
	v_mad_i64_i32 v[84:85], s[28:29], v92, s68, v[108:109]
	v_cvt_pk_bf16_f32 v77, v86, v87
	v_cvt_pk_bf16_f32 v78, v88, v89
	v_cvt_pk_bf16_f32 v79, v90, v91
	v_lshl_add_u64 v[84:85], v[84:85], 0, v[110:111]
	global_store_dwordx4 v[84:85], v[76:79], off
	v_pk_mul_f32 v[70:71], v[70:71], v[154:155] op_sel_hi:[1,0]
	v_pk_mul_f32 v[72:73], v[72:73], v[154:155] op_sel_hi:[1,0]
	v_pk_mul_f32 v[76:77], v[82:83], v[154:155] op_sel_hi:[1,0]
	v_pk_mul_f32 v[78:79], v[80:81], v[154:155] op_sel_hi:[1,0]
	v_pk_mul_f32 v[82:83], v[76:77], v[190:191] op_sel_hi:[1,0]
	v_pk_mul_f32 v[80:81], v[78:79], v[190:191] op_sel_hi:[1,0]
	v_exp_f32_e32 v82, v82
	v_exp_f32_e32 v83, v83
	v_exp_f32_e32 v80, v80
	v_exp_f32_e32 v81, v81
	v_pk_add_f32 v[82:83], v[82:83], v[192:193] op_sel_hi:[1,0]
	v_pk_add_f32 v[80:81], v[80:81], v[192:193] op_sel_hi:[1,0]
	v_rcp_f32_e32 v82, v82
	v_rcp_f32_e32 v83, v83
	v_rcp_f32_e32 v80, v80
	v_rcp_f32_e32 v81, v81
	v_pk_mul_f32 v[68:69], v[68:69], v[154:155] op_sel_hi:[1,0]
	v_pk_mul_f32 v[76:77], v[76:77], v[82:83]
	v_pk_mul_f32 v[74:75], v[74:75], v[154:155] op_sel_hi:[1,0]
	v_pk_mul_f32 v[78:79], v[78:79], v[80:81]
	v_pk_mul_f32 v[70:71], v[70:71], v[76:77]
	v_pk_mul_f32 v[76:77], v[72:73], v[190:191] op_sel_hi:[1,0]
	v_pk_mul_f32 v[68:69], v[68:69], v[78:79]
	v_exp_f32_e32 v76, v76
	v_exp_f32_e32 v77, v77
	v_pk_mul_f32 v[78:79], v[74:75], v[190:191] op_sel_hi:[1,0]
	v_exp_f32_e32 v78, v78
	v_exp_f32_e32 v79, v79
	v_pk_add_f32 v[76:77], v[76:77], v[192:193] op_sel_hi:[1,0]
	v_rcp_f32_e32 v76, v76
	v_rcp_f32_e32 v77, v77
	v_pk_add_f32 v[78:79], v[78:79], v[192:193] op_sel_hi:[1,0]
	v_rcp_f32_e32 v78, v78
	v_rcp_f32_e32 v79, v79
	v_pk_mul_f32 v[64:65], v[64:65], v[154:155] op_sel_hi:[1,0]
	v_pk_mul_f32 v[72:73], v[72:73], v[76:77]
	v_pk_mul_f32 v[66:67], v[66:67], v[154:155] op_sel_hi:[1,0]
	v_pk_mul_f32 v[72:73], v[64:65], v[72:73]
	v_pk_mul_f32 v[64:65], v[74:75], v[78:79]
	v_or_b32_e32 v76, 48, v144
	v_pk_mul_f32 v[74:75], v[66:67], v[64:65]
	v_cvt_pk_bf16_f32 v64, v68, v69
	v_mad_i64_i32 v[68:69], s[28:29], v76, s68, v[108:109]
	v_cvt_pk_bf16_f32 v65, v70, v71
	v_cvt_pk_bf16_f32 v66, v72, v73
	v_cvt_pk_bf16_f32 v67, v74, v75
	v_lshl_add_u64 v[68:69], v[68:69], 0, v[110:111]
	v_pk_mul_f32 v[60:61], v[60:61], v[152:153] op_sel_hi:[1,0]
	global_store_dwordx4 v[68:69], v[64:67], off
	v_pk_mul_f32 v[62:63], v[62:63], v[152:153] op_sel_hi:[1,0]
	v_pk_mul_f32 v[52:53], v[52:53], v[152:153] op_sel_hi:[1,0]
	v_pk_mul_f32 v[64:65], v[60:61], v[190:191] op_sel_hi:[1,0]
	v_exp_f32_e32 v64, v64
	v_exp_f32_e32 v65, v65
	v_pk_mul_f32 v[66:67], v[62:63], v[190:191] op_sel_hi:[1,0]
	v_exp_f32_e32 v66, v66
	v_exp_f32_e32 v67, v67
	v_pk_add_f32 v[64:65], v[64:65], v[192:193] op_sel_hi:[1,0]
	v_rcp_f32_e32 v64, v64
	v_rcp_f32_e32 v65, v65
	v_pk_add_f32 v[66:67], v[66:67], v[192:193] op_sel_hi:[1,0]
	v_rcp_f32_e32 v66, v66
	v_rcp_f32_e32 v67, v67
	v_pk_mul_f32 v[60:61], v[60:61], v[64:65]
	v_pk_mul_f32 v[54:55], v[54:55], v[152:153] op_sel_hi:[1,0]
	v_pk_mul_f32 v[52:53], v[52:53], v[60:61]
	v_pk_mul_f32 v[60:61], v[62:63], v[66:67]
	v_pk_mul_f32 v[56:57], v[56:57], v[152:153] op_sel_hi:[1,0]
	v_pk_mul_f32 v[54:55], v[54:55], v[60:61]
	v_pk_mul_f32 v[58:59], v[58:59], v[152:153] op_sel_hi:[1,0]
	v_pk_mul_f32 v[60:61], v[56:57], v[190:191] op_sel_hi:[1,0]
	v_exp_f32_e32 v60, v60
	v_exp_f32_e32 v61, v61
	v_pk_mul_f32 v[62:63], v[58:59], v[190:191] op_sel_hi:[1,0]
	v_exp_f32_e32 v62, v62
	v_exp_f32_e32 v63, v63
	v_pk_add_f32 v[60:61], v[60:61], v[192:193] op_sel_hi:[1,0]
	v_rcp_f32_e32 v60, v60
	v_rcp_f32_e32 v61, v61
	v_pk_add_f32 v[62:63], v[62:63], v[192:193] op_sel_hi:[1,0]
	v_rcp_f32_e32 v62, v62
	v_rcp_f32_e32 v63, v63
	v_pk_mul_f32 v[44:45], v[44:45], v[152:153] op_sel_hi:[1,0]
	v_pk_mul_f32 v[56:57], v[56:57], v[60:61]
	v_pk_mul_f32 v[46:47], v[46:47], v[152:153] op_sel_hi:[1,0]
	v_pk_mul_f32 v[56:57], v[44:45], v[56:57]
	v_pk_mul_f32 v[44:45], v[58:59], v[62:63]
	v_pk_mul_f32 v[38:39], v[38:39], v[150:151] op_sel_hi:[1,0]
	v_pk_mul_f32 v[58:59], v[46:47], v[44:45]
	v_cvt_pk_bf16_f32 v44, v52, v53
	v_mad_i64_i32 v[52:53], s[28:29], v145, s68, v[108:109]
	v_cvt_pk_bf16_f32 v45, v54, v55
	v_cvt_pk_bf16_f32 v46, v56, v57
	v_cvt_pk_bf16_f32 v47, v58, v59
	v_lshl_add_u64 v[52:53], v[52:53], 0, v[110:111]
	global_store_dwordx4 v[52:53], v[44:47], off
	v_pk_mul_f32 v[40:41], v[40:41], v[150:151] op_sel_hi:[1,0]
	v_pk_mul_f32 v[36:37], v[36:37], v[150:151] op_sel_hi:[1,0]
	v_pk_mul_f32 v[44:45], v[50:51], v[150:151] op_sel_hi:[1,0]
	v_pk_mul_f32 v[46:47], v[48:49], v[150:151] op_sel_hi:[1,0]
	v_pk_mul_f32 v[50:51], v[44:45], v[190:191] op_sel_hi:[1,0]
	v_pk_mul_f32 v[48:49], v[46:47], v[190:191] op_sel_hi:[1,0]
	v_exp_f32_e32 v50, v50
	v_exp_f32_e32 v51, v51
	v_exp_f32_e32 v48, v48
	v_exp_f32_e32 v49, v49
	v_pk_add_f32 v[50:51], v[50:51], v[192:193] op_sel_hi:[1,0]
	v_pk_add_f32 v[48:49], v[48:49], v[192:193] op_sel_hi:[1,0]
	v_rcp_f32_e32 v50, v50
	v_rcp_f32_e32 v51, v51
	v_rcp_f32_e32 v48, v48
	v_rcp_f32_e32 v49, v49
	v_pk_mul_f32 v[42:43], v[42:43], v[150:151] op_sel_hi:[1,0]
	v_pk_mul_f32 v[44:45], v[44:45], v[50:51]
	v_pk_mul_f32 v[46:47], v[46:47], v[48:49]
	v_pk_mul_f32 v[38:39], v[38:39], v[44:45]
	v_pk_mul_f32 v[44:45], v[40:41], v[190:191] op_sel_hi:[1,0]
	v_pk_mul_f32 v[36:37], v[36:37], v[46:47]
	v_exp_f32_e32 v44, v44
	v_exp_f32_e32 v45, v45
	v_pk_mul_f32 v[46:47], v[42:43], v[190:191] op_sel_hi:[1,0]
	v_exp_f32_e32 v46, v46
	v_exp_f32_e32 v47, v47
	v_pk_add_f32 v[44:45], v[44:45], v[192:193] op_sel_hi:[1,0]
	v_rcp_f32_e32 v44, v44
	v_rcp_f32_e32 v45, v45
	v_pk_add_f32 v[46:47], v[46:47], v[192:193] op_sel_hi:[1,0]
	v_rcp_f32_e32 v46, v46
	v_rcp_f32_e32 v47, v47
	v_pk_mul_f32 v[28:29], v[28:29], v[150:151] op_sel_hi:[1,0]
	v_pk_mul_f32 v[40:41], v[40:41], v[44:45]
	v_pk_mul_f32 v[30:31], v[30:31], v[150:151] op_sel_hi:[1,0]
	v_pk_mul_f32 v[40:41], v[28:29], v[40:41]
	v_pk_mul_f32 v[28:29], v[42:43], v[46:47]
	v_add_u32_e32 v44, 0x90, v144
	v_pk_mul_f32 v[42:43], v[30:31], v[28:29]
	v_cvt_pk_bf16_f32 v28, v36, v37
	v_mad_i64_i32 v[36:37], s[28:29], v44, s68, v[108:109]
	v_cvt_pk_bf16_f32 v29, v38, v39
	v_cvt_pk_bf16_f32 v30, v40, v41
	v_cvt_pk_bf16_f32 v31, v42, v43
	v_lshl_add_u64 v[36:37], v[36:37], 0, v[110:111]
	global_store_dwordx4 v[36:37], v[28:31], off
	v_pk_mul_f32 v[22:23], v[22:23], v[148:149] op_sel_hi:[1,0]
	v_pk_mul_f32 v[24:25], v[24:25], v[148:149] op_sel_hi:[1,0]
	v_pk_mul_f32 v[28:29], v[34:35], v[148:149] op_sel_hi:[1,0]
	v_pk_mul_f32 v[30:31], v[32:33], v[148:149] op_sel_hi:[1,0]
	v_pk_mul_f32 v[34:35], v[28:29], v[190:191] op_sel_hi:[1,0]
	v_pk_mul_f32 v[32:33], v[30:31], v[190:191] op_sel_hi:[1,0]
	v_exp_f32_e32 v34, v34
	v_exp_f32_e32 v35, v35
	v_exp_f32_e32 v32, v32
	v_exp_f32_e32 v33, v33
	v_pk_add_f32 v[34:35], v[34:35], v[192:193] op_sel_hi:[1,0]
	v_pk_add_f32 v[32:33], v[32:33], v[192:193] op_sel_hi:[1,0]
	v_rcp_f32_e32 v34, v34
	v_rcp_f32_e32 v35, v35
	v_rcp_f32_e32 v32, v32
	v_rcp_f32_e32 v33, v33
	v_pk_mul_f32 v[20:21], v[20:21], v[148:149] op_sel_hi:[1,0]
	v_pk_mul_f32 v[28:29], v[28:29], v[34:35]
	v_pk_mul_f32 v[26:27], v[26:27], v[148:149] op_sel_hi:[1,0]
	v_pk_mul_f32 v[30:31], v[30:31], v[32:33]
	v_pk_mul_f32 v[22:23], v[22:23], v[28:29]
	v_pk_mul_f32 v[28:29], v[24:25], v[190:191] op_sel_hi:[1,0]
	v_pk_mul_f32 v[20:21], v[20:21], v[30:31]
	v_exp_f32_e32 v28, v28
	v_exp_f32_e32 v29, v29
	v_pk_mul_f32 v[30:31], v[26:27], v[190:191] op_sel_hi:[1,0]
	v_exp_f32_e32 v30, v30
	v_exp_f32_e32 v31, v31
	v_pk_add_f32 v[28:29], v[28:29], v[192:193] op_sel_hi:[1,0]
	v_rcp_f32_e32 v28, v28
	v_rcp_f32_e32 v29, v29
	v_pk_add_f32 v[30:31], v[30:31], v[192:193] op_sel_hi:[1,0]
	v_rcp_f32_e32 v30, v30
	v_rcp_f32_e32 v31, v31
	v_pk_mul_f32 v[12:13], v[12:13], v[148:149] op_sel_hi:[1,0]
	v_pk_mul_f32 v[24:25], v[24:25], v[28:29]
	v_pk_mul_f32 v[14:15], v[14:15], v[148:149] op_sel_hi:[1,0]
	v_pk_mul_f32 v[24:25], v[12:13], v[24:25]
	v_pk_mul_f32 v[12:13], v[26:27], v[30:31]
	v_add_u32_e32 v28, 0xa0, v144
	v_pk_mul_f32 v[26:27], v[14:15], v[12:13]
	v_cvt_pk_bf16_f32 v12, v20, v21
	v_mad_i64_i32 v[20:21], s[28:29], v28, s68, v[108:109]
	v_cvt_pk_bf16_f32 v13, v22, v23
	v_cvt_pk_bf16_f32 v14, v24, v25
	v_cvt_pk_bf16_f32 v15, v26, v27
	v_lshl_add_u64 v[20:21], v[20:21], 0, v[110:111]
	global_store_dwordx4 v[20:21], v[12:15], off
	v_pk_mul_f32 v[6:7], v[6:7], v[146:147] op_sel_hi:[1,0]
	v_pk_mul_f32 v[8:9], v[8:9], v[146:147] op_sel_hi:[1,0]
	v_pk_mul_f32 v[12:13], v[18:19], v[146:147] op_sel_hi:[1,0]
	v_pk_mul_f32 v[14:15], v[16:17], v[146:147] op_sel_hi:[1,0]
	v_pk_mul_f32 v[18:19], v[12:13], v[190:191] op_sel_hi:[1,0]
	v_pk_mul_f32 v[16:17], v[14:15], v[190:191] op_sel_hi:[1,0]
	v_exp_f32_e32 v18, v18
	v_exp_f32_e32 v19, v19
	v_exp_f32_e32 v16, v16
	v_exp_f32_e32 v17, v17
	v_pk_add_f32 v[18:19], v[18:19], v[192:193] op_sel_hi:[1,0]
	v_pk_add_f32 v[16:17], v[16:17], v[192:193] op_sel_hi:[1,0]
	v_rcp_f32_e32 v18, v18
	v_rcp_f32_e32 v19, v19
	v_rcp_f32_e32 v16, v16
	v_rcp_f32_e32 v17, v17
	v_pk_mul_f32 v[4:5], v[4:5], v[146:147] op_sel_hi:[1,0]
	v_pk_mul_f32 v[12:13], v[12:13], v[18:19]
	v_pk_mul_f32 v[10:11], v[10:11], v[146:147] op_sel_hi:[1,0]
	v_pk_mul_f32 v[14:15], v[14:15], v[16:17]
	v_pk_mul_f32 v[6:7], v[6:7], v[12:13]
	v_pk_mul_f32 v[12:13], v[8:9], v[190:191] op_sel_hi:[1,0]
	v_pk_mul_f32 v[4:5], v[4:5], v[14:15]
	v_exp_f32_e32 v12, v12
	v_exp_f32_e32 v13, v13
	v_pk_mul_f32 v[14:15], v[10:11], v[190:191] op_sel_hi:[1,0]
	v_exp_f32_e32 v14, v14
	v_exp_f32_e32 v15, v15
	v_pk_add_f32 v[12:13], v[12:13], v[192:193] op_sel_hi:[1,0]
	v_rcp_f32_e32 v12, v12
	v_rcp_f32_e32 v13, v13
	v_pk_add_f32 v[14:15], v[14:15], v[192:193] op_sel_hi:[1,0]
	v_rcp_f32_e32 v14, v14
	v_rcp_f32_e32 v15, v15
	v_pk_mul_f32 v[0:1], v[0:1], v[146:147] op_sel_hi:[1,0]
	v_pk_mul_f32 v[8:9], v[8:9], v[12:13]
	v_pk_mul_f32 v[2:3], v[2:3], v[146:147] op_sel_hi:[1,0]
	v_pk_mul_f32 v[8:9], v[0:1], v[8:9]
	v_pk_mul_f32 v[0:1], v[10:11], v[14:15]
	v_add_u32_e32 v12, 0xb0, v144
	v_pk_mul_f32 v[10:11], v[2:3], v[0:1]
	v_cvt_pk_bf16_f32 v0, v4, v5
	v_mad_i64_i32 v[4:5], s[28:29], v12, s68, v[108:109]
	v_cvt_pk_bf16_f32 v1, v6, v7
	v_cvt_pk_bf16_f32 v2, v8, v9
	v_cvt_pk_bf16_f32 v3, v10, v11
	v_lshl_add_u64 v[4:5], v[4:5], 0, v[110:111]
	global_store_dwordx4 v[4:5], v[0:3], off
	s_cbranch_scc1 .LBB0_1226
	s_waitcnt vmcnt(0)
	buffer_wbl2 sc1
	s_waitcnt vmcnt(0)
	s_waitcnt vmcnt(0)
	s_and_saveexec_b64 s[28:29], s[4:5]
	s_cbranch_execz .LBB0_1225
	s_mov_b64 s[30:31], exec
	v_mbcnt_lo_u32_b32 v0, s30, 0
	v_mbcnt_hi_u32_b32 v0, s31, v0
	v_cmp_eq_u32_e32 vcc, 0, v0
	s_and_b64 s[34:35], exec, vcc
	s_mov_b64 exec, s[34:35]
	s_cbranch_execz .LBB0_1225
	s_bcnt1_i32_b64 s11, s[30:31]
	v_mov_b32_e32 v0, s11
	global_atomic_add v129, v0, s[8:9]
	s_branch .LBB0_1225
